# v11 + sub-LN combine phase: the eight O-segment loads of a row issued together with counted waits instead of one load-wait round trip per head
# speedup vs baseline: 1.0108x; 1.0020x over previous
; __device__ __forceinline__ unsigned cvtpk(float lo, float hi) { unsigned r; asm volatile("v_cvt_pk_bf16_f32 %0, %1, %2" : "=v"(r) : "v"(lo), "v"(hi)); return r; }
; __device__ __forceinline__ void phase_combine(const Params& p, const Ctx& c, int l, bool last) {
;     ...
;   for (int row = c.gwave; row < TT; row += c.nwave) { const int t = row % TPB; if (last && t < CTXL) continue;
;     const bf16_t* orow = O + (size_t)row * DM; bf16_t* crow_ = Cat + (size_t)row * DM;
; #pragma unroll
;     for (int h = 0; h < 4; ++h) { const u32x2 a = *(const u32x2*)(orow + (h * 2) * 256 + c.lane * 4), bq = *(const u32x2*)(orow + (h * 2 + 1) * 256 + c.lane * 4);
;       f32x4 o; o[0] = __uint_as_float(a[0] << 16) - lam * __uint_as_float(bq[0] << 16); o[1] = __uint_as_float(a[0] & 0xffff0000u) - lam * __uint_as_float(bq[0] & 0xffff0000u);
;       o[2] = __uint_as_float(a[1] << 16) - lam * __uint_as_float(bq[1] << 16); o[3] = __uint_as_float(a[1] & 0xffff0000u) - lam * __uint_as_float(bq[1] & 0xffff0000u);
;       const float ss = wave_sum(o[0] * o[0] + o[1] * o[1] + o[2] * o[2] + o[3] * o[3]); const float r = rsqrtf(ss * (1.f / 256.f) + 1e-5f) * (1.f - lam_init);
;       o = o * r * gs; u32x2 w = {cvtpk(o[0], o[1]), cvtpk(o[2], o[3])}; *(u32x2*)(crow_ + h * 256 + c.lane * 4) = w; }
.LBB0_725:
	v_mul_hi_i32 v7, v6, s94
	v_lshrrev_b32_e32 v12, 31, v7
	v_ashrrev_i32_e32 v7, 11, v7
	v_add_u32_e32 v7, v7, v12
	v_mul_i32_i24_e32 v7, 0x1100, v7
	v_sub_u32_e32 v7, v6, v7
	v_cmp_lt_i32_e32 vcc, s27, v7
	s_or_b64 s[0:1], s[52:53], vcc
	s_and_saveexec_b64 s[10:11], s[0:1]
	s_cbranch_execz .LBB0_724
	s_mov_b32 s4, 0x800000
	v_add_co_u32_e32 v12, vcc, 0xeb401000, v10
	s_nop 1
	v_addc_co_u32_e32 v13, vcc, -1, v11, vcc
	global_load_dwordx2 v[24:25], v[12:13], off offset:-4096
	global_load_dwordx2 v[26:27], v[12:13], off offset:-3584
	global_load_dwordx2 v[28:29], v[12:13], off offset:-3072
	global_load_dwordx2 v[30:31], v[12:13], off offset:-2560
	global_load_dwordx2 v[32:33], v[12:13], off offset:-2048
	global_load_dwordx2 v[34:35], v[12:13], off offset:-1536
	global_load_dwordx2 v[36:37], v[12:13], off offset:-1024
	global_load_dwordx2 v[38:39], v[12:13], off offset:-512
	s_waitcnt vmcnt(6)
	v_lshlrev_b32_e32 v18, 16, v24
	v_and_b32_e32 v19, 0xffff0000, v24
	v_lshlrev_b32_e32 v14, 16, v25
	v_and_b32_e32 v15, 0xffff0000, v25
	v_lshlrev_b32_e32 v20, 16, v26
	v_and_b32_e32 v21, 0xffff0000, v26
	v_lshlrev_b32_e32 v16, 16, v27
	v_and_b32_e32 v17, 0xffff0000, v27
	v_pk_fma_f32 v[18:19], v[8:9], v[20:21], v[18:19] neg_lo:[1,0,0] neg_hi:[1,0,0]
	v_pk_fma_f32 v[14:15], v[8:9], v[16:17], v[14:15] neg_lo:[1,0,0] neg_hi:[1,0,0]
	v_pk_mul_f32 v[16:17], v[18:19], v[18:19]
	v_pk_mul_f32 v[20:21], v[14:15], v[14:15]
	v_add_f32_e32 v7, v16, v17
	v_add_f32_e32 v7, v20, v7
	v_add_f32_e32 v7, v21, v7
	s_nop 1
	v_add_f32_dpp v7, v7, v7 quad_perm:[1,0,3,2] row_mask:0xf bank_mask:0xf bound_ctrl:1
	s_nop 1
	v_add_f32_dpp v7, v7, v7 quad_perm:[2,3,0,1] row_mask:0xf bank_mask:0xf bound_ctrl:1
	s_nop 1
	v_add_f32_dpp v7, v7, v7 row_half_mirror row_mask:0xf bank_mask:0xf bound_ctrl:1
	s_nop 1
	v_add_f32_dpp v7, v7, v7 row_mirror row_mask:0xf bank_mask:0xf bound_ctrl:1
	s_nop 0
	v_readlane_b32 s2, v7, 16
	v_readlane_b32 s3, v7, 48
	v_readlane_b32 s0, v7, 0
	v_readlane_b32 s1, v7, 32
	v_mov_b32_e32 v16, s2
	v_mov_b32_e32 v17, s3
	v_pk_add_f32 v[16:17], s[0:1], v[16:17]
	s_nop 0
	v_add_f32_e32 v7, v16, v17
	v_fmamk_f32 v7, v7, 0x3b800000, v226
	v_mul_f32_e32 v16, 0x4b800000, v7
	v_cmp_gt_f32_e32 vcc, s4, v7
	s_nop 1
	v_cndmask_b32_e32 v7, v7, v16, vcc
	v_rsq_f32_e32 v7, v7
	s_nop 0
	v_mul_f32_e32 v16, 0x45800000, v7
	v_cndmask_b32_e32 v7, v7, v16, vcc
	v_mul_f32_e32 v16, v1, v7
	v_pk_mul_f32 v[18:19], v[18:19], v[16:17] op_sel_hi:[1,0]
	v_pk_mul_f32 v[14:15], v[14:15], v[16:17] op_sel_hi:[1,0]
	v_pk_mul_f32 v[16:17], v[2:3], v[18:19]
	v_pk_mul_f32 v[14:15], v[4:5], v[14:15]
	v_cvt_pk_bf16_f32 v16, v16, v17
	s_nop 0
	v_cvt_pk_bf16_f32 v17, v14, v15
	s_waitcnt vmcnt(4)
	v_lshlrev_b32_e32 v20, 16, v28
	v_and_b32_e32 v21, 0xffff0000, v28
	v_lshlrev_b32_e32 v22, 16, v30
	v_and_b32_e32 v23, 0xffff0000, v30
	v_lshlrev_b32_e32 v14, 16, v29
	v_and_b32_e32 v15, 0xffff0000, v29
	v_lshlrev_b32_e32 v18, 16, v31
	v_and_b32_e32 v19, 0xffff0000, v31
	v_pk_fma_f32 v[20:21], v[8:9], v[22:23], v[20:21] neg_lo:[1,0,0] neg_hi:[1,0,0]
	v_pk_fma_f32 v[14:15], v[8:9], v[18:19], v[14:15] neg_lo:[1,0,0] neg_hi:[1,0,0]
	v_pk_mul_f32 v[18:19], v[20:21], v[20:21]
	v_pk_mul_f32 v[22:23], v[14:15], v[14:15]
	v_add_f32_e32 v7, v18, v19
	v_add_f32_e32 v7, v22, v7
	v_add_f32_e32 v7, v23, v7
	global_store_dwordx2 v[10:11], v[16:17], off
	s_nop 0
	v_add_f32_dpp v7, v7, v7 quad_perm:[1,0,3,2] row_mask:0xf bank_mask:0xf bound_ctrl:1
	s_nop 1
	v_add_f32_dpp v7, v7, v7 quad_perm:[2,3,0,1] row_mask:0xf bank_mask:0xf bound_ctrl:1
	s_nop 1
	v_add_f32_dpp v7, v7, v7 row_half_mirror row_mask:0xf bank_mask:0xf bound_ctrl:1
	s_nop 1
	v_add_f32_dpp v7, v7, v7 row_mirror row_mask:0xf bank_mask:0xf bound_ctrl:1
	s_nop 0
	v_readlane_b32 s2, v7, 16
	v_readlane_b32 s3, v7, 48
	v_readlane_b32 s0, v7, 0
	v_readlane_b32 s1, v7, 32
	v_mov_b32_e32 v18, s2
	v_mov_b32_e32 v19, s3
	v_pk_add_f32 v[18:19], s[0:1], v[18:19]
	s_nop 0
	v_add_f32_e32 v7, v18, v19
	v_fmamk_f32 v7, v7, 0x3b800000, v226
	v_mul_f32_e32 v18, 0x4b800000, v7
	v_cmp_gt_f32_e32 vcc, s4, v7
	s_nop 1
	v_cndmask_b32_e32 v7, v7, v18, vcc
	v_rsq_f32_e32 v7, v7
	s_nop 0
	v_mul_f32_e32 v16, 0x45800000, v7
	v_cndmask_b32_e32 v7, v7, v16, vcc
	v_mul_f32_e32 v16, v1, v7
	v_pk_mul_f32 v[18:19], v[20:21], v[16:17] op_sel_hi:[1,0]
	v_pk_mul_f32 v[14:15], v[14:15], v[16:17] op_sel_hi:[1,0]
	v_pk_mul_f32 v[16:17], v[2:3], v[18:19]
	v_pk_mul_f32 v[14:15], v[4:5], v[14:15]
	v_cvt_pk_bf16_f32 v16, v16, v17
	s_nop 0
	v_cvt_pk_bf16_f32 v17, v14, v15
	s_waitcnt vmcnt(3)
; __device__ __forceinline__ unsigned cvtpk(float lo, float hi) { unsigned r; asm volatile("v_cvt_pk_bf16_f32 %0, %1, %2" : "=v"(r) : "v"(lo), "v"(hi)); return r; }
; __device__ __forceinline__ void phase_combine(const Params& p, const Ctx& c, int l, bool last) {
;     ...
;     for (int h = 0; h < 4; ++h) { const u32x2 a = *(const u32x2*)(orow + (h * 2) * 256 + c.lane * 4), bq = *(const u32x2*)(orow + (h * 2 + 1) * 256 + c.lane * 4);
;       f32x4 o; o[0] = __uint_as_float(a[0] << 16) - lam * __uint_as_float(bq[0] << 16); o[1] = __uint_as_float(a[0] & 0xffff0000u) - lam * __uint_as_float(bq[0] & 0xffff0000u);
;       o[2] = __uint_as_float(a[1] << 16) - lam * __uint_as_float(bq[1] << 16); o[3] = __uint_as_float(a[1] & 0xffff0000u) - lam * __uint_as_float(bq[1] & 0xffff0000u);
;       const float ss = wave_sum(o[0] * o[0] + o[1] * o[1] + o[2] * o[2] + o[3] * o[3]); const float r = rsqrtf(ss * (1.f / 256.f) + 1e-5f) * (1.f - lam_init);
;       o = o * r * gs; u32x2 w = {cvtpk(o[0], o[1]), cvtpk(o[2], o[3])}; *(u32x2*)(crow_ + h * 256 + c.lane * 4) = w; }
	v_lshlrev_b32_e32 v20, 16, v32
	v_and_b32_e32 v21, 0xffff0000, v32
	v_lshlrev_b32_e32 v22, 16, v34
	v_and_b32_e32 v23, 0xffff0000, v34
	v_lshlrev_b32_e32 v14, 16, v33
	v_and_b32_e32 v15, 0xffff0000, v33
	v_lshlrev_b32_e32 v18, 16, v35
	v_and_b32_e32 v19, 0xffff0000, v35
	v_pk_fma_f32 v[20:21], v[8:9], v[22:23], v[20:21] neg_lo:[1,0,0] neg_hi:[1,0,0]
	v_pk_fma_f32 v[14:15], v[8:9], v[18:19], v[14:15] neg_lo:[1,0,0] neg_hi:[1,0,0]
	v_pk_mul_f32 v[18:19], v[20:21], v[20:21]
	v_pk_mul_f32 v[22:23], v[14:15], v[14:15]
	v_add_f32_e32 v7, v18, v19
	v_add_f32_e32 v7, v22, v7
	v_add_f32_e32 v7, v23, v7
	global_store_dwordx2 v[10:11], v[16:17], off offset:512
	s_nop 0
	v_add_f32_dpp v7, v7, v7 quad_perm:[1,0,3,2] row_mask:0xf bank_mask:0xf bound_ctrl:1
	s_nop 1
	v_add_f32_dpp v7, v7, v7 quad_perm:[2,3,0,1] row_mask:0xf bank_mask:0xf bound_ctrl:1
	s_nop 1
	v_add_f32_dpp v7, v7, v7 row_half_mirror row_mask:0xf bank_mask:0xf bound_ctrl:1
	s_nop 1
	v_add_f32_dpp v7, v7, v7 row_mirror row_mask:0xf bank_mask:0xf bound_ctrl:1
	s_nop 0
	v_readlane_b32 s2, v7, 16
	v_readlane_b32 s3, v7, 48
	v_readlane_b32 s0, v7, 0
	v_readlane_b32 s1, v7, 32
	v_mov_b32_e32 v18, s2
	v_mov_b32_e32 v19, s3
	v_pk_add_f32 v[18:19], s[0:1], v[18:19]
	s_nop 0
	v_add_f32_e32 v7, v18, v19
	v_fmamk_f32 v7, v7, 0x3b800000, v226
	v_mul_f32_e32 v18, 0x4b800000, v7
	v_cmp_gt_f32_e32 vcc, s4, v7
	s_nop 1
	v_cndmask_b32_e32 v7, v7, v18, vcc
	v_rsq_f32_e32 v7, v7
	s_nop 0
	v_mul_f32_e32 v16, 0x45800000, v7
	v_cndmask_b32_e32 v7, v7, v16, vcc
	v_mul_f32_e32 v16, v1, v7
	v_pk_mul_f32 v[18:19], v[20:21], v[16:17] op_sel_hi:[1,0]
	v_pk_mul_f32 v[14:15], v[14:15], v[16:17] op_sel_hi:[1,0]
	v_pk_mul_f32 v[16:17], v[2:3], v[18:19]
	v_pk_mul_f32 v[14:15], v[4:5], v[14:15]
	v_cvt_pk_bf16_f32 v16, v16, v17
	s_nop 0
	v_cvt_pk_bf16_f32 v17, v14, v15
	s_waitcnt vmcnt(2)
	v_lshlrev_b32_e32 v18, 16, v36
	v_and_b32_e32 v19, 0xffff0000, v36
	v_lshlrev_b32_e32 v20, 16, v38
	v_and_b32_e32 v21, 0xffff0000, v38
	v_lshlrev_b32_e32 v14, 16, v37
	v_and_b32_e32 v15, 0xffff0000, v37
	v_lshlrev_b32_e32 v12, 16, v39
	v_and_b32_e32 v13, 0xffff0000, v39
	v_pk_fma_f32 v[18:19], v[8:9], v[20:21], v[18:19] neg_lo:[1,0,0] neg_hi:[1,0,0]
	v_pk_fma_f32 v[12:13], v[8:9], v[12:13], v[14:15] neg_lo:[1,0,0] neg_hi:[1,0,0]
	v_pk_mul_f32 v[14:15], v[18:19], v[18:19]
	v_pk_mul_f32 v[20:21], v[12:13], v[12:13]
	v_add_f32_e32 v7, v14, v15
	v_add_f32_e32 v7, v20, v7
	v_add_f32_e32 v7, v21, v7
	global_store_dwordx2 v[10:11], v[16:17], off offset:1024
	s_nop 0
	v_add_f32_dpp v7, v7, v7 quad_perm:[1,0,3,2] row_mask:0xf bank_mask:0xf bound_ctrl:1
	s_nop 1
	v_add_f32_dpp v7, v7, v7 quad_perm:[2,3,0,1] row_mask:0xf bank_mask:0xf bound_ctrl:1
	s_nop 1
	v_add_f32_dpp v7, v7, v7 row_half_mirror row_mask:0xf bank_mask:0xf bound_ctrl:1
	s_nop 1
	v_add_f32_dpp v7, v7, v7 row_mirror row_mask:0xf bank_mask:0xf bound_ctrl:1
	s_nop 0
	v_readlane_b32 s2, v7, 16
	v_readlane_b32 s3, v7, 48
	v_readlane_b32 s0, v7, 0
	v_readlane_b32 s1, v7, 32
	v_mov_b32_e32 v14, s2
	v_mov_b32_e32 v15, s3
	v_pk_add_f32 v[14:15], s[0:1], v[14:15]
	s_nop 0
	v_add_f32_e32 v7, v14, v15
	v_fmamk_f32 v7, v7, 0x3b800000, v226
	v_mul_f32_e32 v14, 0x4b800000, v7
	v_cmp_gt_f32_e32 vcc, s4, v7
	s_nop 1
	v_cndmask_b32_e32 v7, v7, v14, vcc
	v_rsq_f32_e32 v7, v7
	s_nop 0
	v_mul_f32_e32 v14, 0x45800000, v7
	v_cndmask_b32_e32 v7, v7, v14, vcc
	v_mul_f32_e32 v14, v1, v7
	v_pk_mul_f32 v[16:17], v[18:19], v[14:15] op_sel_hi:[1,0]
	v_pk_mul_f32 v[12:13], v[12:13], v[14:15] op_sel_hi:[1,0]
	v_pk_mul_f32 v[14:15], v[2:3], v[16:17]
	v_pk_mul_f32 v[12:13], v[4:5], v[12:13]
	v_cvt_pk_bf16_f32 v14, v14, v15
	s_nop 0
	v_cvt_pk_bf16_f32 v15, v12, v13
	global_store_dwordx2 v[10:11], v[14:15], off offset:1536
	s_branch .LBB0_724
